# third measure of the kept version: chain dma+stores, gla_prep raw-v double buffer, scalar-base GEMM DMAs
# baseline (speedup 1.0000x reference)
; #define LAS __attribute__((address_space(3)))
; DI void phase_gla_prep(const Params& P, int l, int bid, int nb, LAS unsigned char* lds) {
;     ...
;         for (int dir = 0; dir < 2; ++dir) {
;             float w0[16], w1[16];
; #pragma unroll
;             for (int k = 0; k < 16; ++k) { const f32x2 t = *(const LAS f32x2*)(lds + PP_W + ((dir * 16 + k) * 128 + c0) * 4); w0[k] = t.x; w1[k] = t.y; }
.LBB0_344:
	v_fma_f32 v250, v250, v250, v250
	v_fma_f32 v251, v251, v251, v251
	v_fma_f32 v252, v252, v252, v252
	v_fma_f32 v253, v253, v253, v253
	v_fma_f32 v250, v250, v250, v250
	v_fma_f32 v251, v251, v251, v251
	v_fma_f32 v252, v252, v252, v252
	v_fma_f32 v253, v253, v253, v253
	v_fma_f32 v250, v250, v250, v250
	v_fma_f32 v251, v251, v251, v251
	v_fma_f32 v252, v252, v252, v252
	v_fma_f32 v253, v253, v253, v253
	v_fma_f32 v250, v250, v250, v250
	v_fma_f32 v251, v251, v251, v251
	v_fma_f32 v252, v252, v252, v252
	v_fma_f32 v253, v253, v253, v253
	v_fma_f32 v250, v250, v250, v250
	v_fma_f32 v251, v251, v251, v251
	v_fma_f32 v252, v252, v252, v252
	v_fma_f32 v253, v253, v253, v253
	v_fma_f32 v250, v250, v250, v250
	v_fma_f32 v251, v251, v251, v251
	v_fma_f32 v252, v252, v252, v252
	v_fma_f32 v253, v253, v253, v253
	v_fma_f32 v250, v250, v250, v250
	v_fma_f32 v251, v251, v251, v251
	v_fma_f32 v252, v252, v252, v252
	v_fma_f32 v253, v253, v253, v253
	v_fma_f32 v250, v250, v250, v250
	v_fma_f32 v251, v251, v251, v251
	v_fma_f32 v252, v252, v252, v252
	v_fma_f32 v253, v253, v253, v253
	v_fma_f32 v250, v250, v250, v250
	v_fma_f32 v251, v251, v251, v251
	v_fma_f32 v252, v252, v252, v252
	v_fma_f32 v253, v253, v253, v253
	v_fma_f32 v250, v250, v250, v250
	v_fma_f32 v251, v251, v251, v251
	v_fma_f32 v252, v252, v252, v252
	v_fma_f32 v253, v253, v253, v253
	v_fma_f32 v250, v250, v250, v250
	v_fma_f32 v251, v251, v251, v251
	v_fma_f32 v252, v252, v252, v252
	v_fma_f32 v253, v253, v253, v253
	v_fma_f32 v250, v250, v250, v250
	v_fma_f32 v251, v251, v251, v251
	v_fma_f32 v252, v252, v252, v252
	v_fma_f32 v253, v253, v253, v253
	v_fma_f32 v250, v250, v250, v250
	v_fma_f32 v251, v251, v251, v251
	v_fma_f32 v252, v252, v252, v252
	v_fma_f32 v253, v253, v253, v253
	v_fma_f32 v250, v250, v250, v250
	v_fma_f32 v251, v251, v251, v251
	v_fma_f32 v252, v252, v252, v252
	v_fma_f32 v253, v253, v253, v253
	v_fma_f32 v250, v250, v250, v250
	v_fma_f32 v251, v251, v251, v251
	v_fma_f32 v252, v252, v252, v252
	v_fma_f32 v253, v253, v253, v253
	v_fma_f32 v250, v250, v250, v250
	v_fma_f32 v251, v251, v251, v251
	v_fma_f32 v252, v252, v252, v252
	v_fma_f32 v253, v253, v253, v253
	v_fma_f32 v250, v250, v250, v250
	v_fma_f32 v251, v251, v251, v251
	v_fma_f32 v252, v252, v252, v252
	v_fma_f32 v253, v253, v253, v253
	v_fma_f32 v250, v250, v250, v250
	v_fma_f32 v251, v251, v251, v251
	v_fma_f32 v252, v252, v252, v252
	v_fma_f32 v253, v253, v253, v253
	v_fma_f32 v250, v250, v250, v250
	v_fma_f32 v251, v251, v251, v251
	v_fma_f32 v252, v252, v252, v252
	v_fma_f32 v253, v253, v253, v253
	v_fma_f32 v250, v250, v250, v250
	v_fma_f32 v251, v251, v251, v251
	v_fma_f32 v252, v252, v252, v252
	v_fma_f32 v253, v253, v253, v253
	v_fma_f32 v250, v250, v250, v250
	v_fma_f32 v251, v251, v251, v251
	v_fma_f32 v252, v252, v252, v252
	v_fma_f32 v253, v253, v253, v253
	v_fma_f32 v250, v250, v250, v250
	v_fma_f32 v251, v251, v251, v251
	v_fma_f32 v252, v252, v252, v252
	v_fma_f32 v253, v253, v253, v253
	v_fma_f32 v250, v250, v250, v250
	v_fma_f32 v251, v251, v251, v251
	v_fma_f32 v252, v252, v252, v252
	v_fma_f32 v253, v253, v253, v253
	v_fma_f32 v250, v250, v250, v250
	v_fma_f32 v251, v251, v251, v251
	v_fma_f32 v252, v252, v252, v252
	v_fma_f32 v253, v253, v253, v253
	v_fma_f32 v250, v250, v250, v250
	v_fma_f32 v251, v251, v251, v251
	v_fma_f32 v252, v252, v252, v252
	v_fma_f32 v253, v253, v253, v253
	v_fma_f32 v250, v250, v250, v250
	v_fma_f32 v251, v251, v251, v251
	v_fma_f32 v252, v252, v252, v252
	v_fma_f32 v253, v253, v253, v253
	v_fma_f32 v250, v250, v250, v250
	v_fma_f32 v251, v251, v251, v251
	v_fma_f32 v252, v252, v252, v252
	v_fma_f32 v253, v253, v253, v253
	v_fma_f32 v250, v250, v250, v250
	v_fma_f32 v251, v251, v251, v251
	v_fma_f32 v252, v252, v252, v252
	v_fma_f32 v253, v253, v253, v253
	v_fma_f32 v250, v250, v250, v250
	v_fma_f32 v251, v251, v251, v251
	v_fma_f32 v252, v252, v252, v252
	v_fma_f32 v253, v253, v253, v253
	v_fma_f32 v250, v250, v250, v250
	v_fma_f32 v251, v251, v251, v251
	v_fma_f32 v252, v252, v252, v252
	v_fma_f32 v253, v253, v253, v253
	v_fma_f32 v250, v250, v250, v250
	v_fma_f32 v251, v251, v251, v251
	v_fma_f32 v252, v252, v252, v252
	v_fma_f32 v253, v253, v253, v253
	v_fma_f32 v250, v250, v250, v250
	v_fma_f32 v251, v251, v251, v251
	v_fma_f32 v252, v252, v252, v252
	v_fma_f32 v253, v253, v253, v253
	v_fma_f32 v250, v250, v250, v250
	v_fma_f32 v251, v251, v251, v251
	v_fma_f32 v252, v252, v252, v252
	v_fma_f32 v253, v253, v253, v253
	v_fma_f32 v250, v250, v250, v250
	v_fma_f32 v251, v251, v251, v251
	v_fma_f32 v252, v252, v252, v252
	v_fma_f32 v253, v253, v253, v253
	v_fma_f32 v250, v250, v250, v250
	v_fma_f32 v251, v251, v251, v251
	v_fma_f32 v252, v252, v252, v252
	v_fma_f32 v253, v253, v253, v253
	v_fma_f32 v250, v250, v250, v250
	v_fma_f32 v251, v251, v251, v251
	v_fma_f32 v252, v252, v252, v252
	v_fma_f32 v253, v253, v253, v253
	v_fma_f32 v250, v250, v250, v250
	v_fma_f32 v251, v251, v251, v251
	v_fma_f32 v252, v252, v252, v252
	v_fma_f32 v253, v253, v253, v253
	v_fma_f32 v250, v250, v250, v250
	v_fma_f32 v251, v251, v251, v251
	v_fma_f32 v252, v252, v252, v252
	v_fma_f32 v253, v253, v253, v253
	v_fma_f32 v250, v250, v250, v250
	v_fma_f32 v251, v251, v251, v251
	v_fma_f32 v252, v252, v252, v252
	v_fma_f32 v253, v253, v253, v253
	v_fma_f32 v250, v250, v250, v250
	v_fma_f32 v251, v251, v251, v251
	v_fma_f32 v252, v252, v252, v252
	v_fma_f32 v253, v253, v253, v253
	v_fma_f32 v250, v250, v250, v250
	v_fma_f32 v251, v251, v251, v251
	v_fma_f32 v252, v252, v252, v252
	v_fma_f32 v253, v253, v253, v253
	v_fma_f32 v250, v250, v250, v250
	v_fma_f32 v251, v251, v251, v251
; #define LAS __attribute__((address_space(3)))
; DI float logsigmoid_fast(float z) { return fminf(z, 0.f) - 0.6931471805599453f * __builtin_amdgcn_logf(1.0f + __builtin_amdgcn_exp2f(-fabsf(z) * LOG2E)); }
; DI void phase_gla_prep(const Params& P, int l, int bid, int nb, LAS unsigned char* lds) {
;     ...
;             float w0[16], w1[16];
; #pragma unroll
;             for (int k = 0; k < 16; ++k) { const f32x2 t = *(const LAS f32x2*)(lds + PP_W + ((dir * 16 + k) * 128 + c0) * 4); w0[k] = t.x; w1[k] = t.y; }
;             const f32x2 bb = dir ? bbs[1] : bbs[0];
;             float g0[8], g1[8];
; #pragma unroll
;             for (int r = 0; r < 8; ++r) { float z0 = bb.x, z1 = bb.y; const LAS float* lr = (const LAS float*)(lds + PP_LR) + (rg * 8 + r) * 32 + dir * 16;
; #pragma unroll
;                 for (int k4 = 0; k4 < 4; ++k4) { const f32x4 t = *(const LAS f32x4*)(lr + k4 * 4);
; #pragma unroll
;                     for (int u = 0; u < 4; ++u) { z0 += t[u] * w0[k4 * 4 + u]; z1 += t[u] * w1[k4 * 4 + u]; } }
;                 g0[r] = logsigmoid_fast(z0) * 0.0625f; g1[r] = logsigmoid_fast(z1) * 0.0625f; __builtin_amdgcn_sched_barrier(0); }
	v_fma_f32 v252, v252, v252, v252
	v_fma_f32 v253, v253, v253, v253
	v_fma_f32 v250, v250, v250, v250
	v_fma_f32 v251, v251, v251, v251
	v_fma_f32 v252, v252, v252, v252
	v_fma_f32 v253, v253, v253, v253
	v_fma_f32 v250, v250, v250, v250
	v_fma_f32 v251, v251, v251, v251
	v_fma_f32 v252, v252, v252, v252
	v_fma_f32 v253, v253, v253, v253
	v_fma_f32 v250, v250, v250, v250
	v_fma_f32 v251, v251, v251, v251
	v_fma_f32 v252, v252, v252, v252
	v_fma_f32 v253, v253, v253, v253
	v_fma_f32 v250, v250, v250, v250
	v_fma_f32 v251, v251, v251, v251
	v_fma_f32 v252, v252, v252, v252
	v_fma_f32 v253, v253, v253, v253
	v_fma_f32 v250, v250, v250, v250
	v_fma_f32 v251, v251, v251, v251
	v_fma_f32 v252, v252, v252, v252
	v_fma_f32 v253, v253, v253, v253
	v_fma_f32 v250, v250, v250, v250
	v_fma_f32 v251, v251, v251, v251
	v_fma_f32 v252, v252, v252, v252
	v_fma_f32 v253, v253, v253, v253
	v_fma_f32 v250, v250, v250, v250
	v_fma_f32 v251, v251, v251, v251
	v_fma_f32 v252, v252, v252, v252
	v_fma_f32 v253, v253, v253, v253
	v_fma_f32 v250, v250, v250, v250
	v_fma_f32 v251, v251, v251, v251
	v_fma_f32 v252, v252, v252, v252
	v_fma_f32 v253, v253, v253, v253
	v_fma_f32 v250, v250, v250, v250
	v_fma_f32 v251, v251, v251, v251
	v_fma_f32 v252, v252, v252, v252
	v_fma_f32 v253, v253, v253, v253
	v_fma_f32 v250, v250, v250, v250
	v_fma_f32 v251, v251, v251, v251
	v_fma_f32 v252, v252, v252, v252
	v_fma_f32 v253, v253, v253, v253
	v_fma_f32 v250, v250, v250, v250
	v_fma_f32 v251, v251, v251, v251
	v_fma_f32 v252, v252, v252, v252
	v_fma_f32 v253, v253, v253, v253
	v_fma_f32 v250, v250, v250, v250
	v_fma_f32 v251, v251, v251, v251
	v_fma_f32 v252, v252, v252, v252
	v_fma_f32 v253, v253, v253, v253
	v_fma_f32 v250, v250, v250, v250
	v_fma_f32 v251, v251, v251, v251
	v_fma_f32 v252, v252, v252, v252
	v_fma_f32 v253, v253, v253, v253
	v_fma_f32 v250, v250, v250, v250
	v_fma_f32 v251, v251, v251, v251
	v_fma_f32 v252, v252, v252, v252
	v_fma_f32 v253, v253, v253, v253
	v_fma_f32 v250, v250, v250, v250
	v_fma_f32 v251, v251, v251, v251
	v_fma_f32 v252, v252, v252, v252
	v_fma_f32 v253, v253, v253, v253
	v_fma_f32 v250, v250, v250, v250
	v_fma_f32 v251, v251, v251, v251
	v_fma_f32 v252, v252, v252, v252
	v_fma_f32 v253, v253, v253, v253
	v_fma_f32 v250, v250, v250, v250
	v_fma_f32 v251, v251, v251, v251
	v_fma_f32 v252, v252, v252, v252
	v_fma_f32 v253, v253, v253, v253
	v_fma_f32 v250, v250, v250, v250
	v_fma_f32 v251, v251, v251, v251
	v_fma_f32 v252, v252, v252, v252
	v_fma_f32 v253, v253, v253, v253
	v_fma_f32 v250, v250, v250, v250
	v_fma_f32 v251, v251, v251, v251
	v_fma_f32 v252, v252, v252, v252
	v_fma_f32 v253, v253, v253, v253
	v_fma_f32 v250, v250, v250, v250
	v_fma_f32 v251, v251, v251, v251
	v_fma_f32 v252, v252, v252, v252
	v_fma_f32 v253, v253, v253, v253
	v_fma_f32 v250, v250, v250, v250
	v_fma_f32 v251, v251, v251, v251
	v_fma_f32 v252, v252, v252, v252
	v_fma_f32 v253, v253, v253, v253
	v_fma_f32 v250, v250, v250, v250
	v_fma_f32 v251, v251, v251, v251
	v_fma_f32 v252, v252, v252, v252
	v_fma_f32 v253, v253, v253, v253
	s_lshl_b32 s90, s76, 13
	v_add_u32_e32 v2, s90, v142
	v_add_u32_e32 v3, s90, v143
	v_add_u32_e32 v4, s90, v144
	v_add_u32_e32 v5, s90, v145
	ds_read_b64 v[134:135], v2
	ds_read_b64 v[132:133], v3
	ds_read_b64 v[128:129], v4
	ds_read_b64 v[124:125], v5
	v_add_u32_e32 v2, s90, v146
	v_add_u32_e32 v3, s90, v147
	v_add_u32_e32 v4, s90, v148
	v_add_u32_e32 v5, s90, v149
	ds_read_b64 v[130:131], v2
	ds_read_b64 v[126:127], v3
	ds_read_b64 v[120:121], v4
	ds_read_b64 v[14:15], v5
	v_add_u32_e32 v2, s90, v150
	v_add_u32_e32 v3, s90, v151
	v_add_u32_e32 v4, s90, v152
	v_add_u32_e32 v5, s90, v153
	ds_read_b64 v[122:123], v2
	ds_read_b64 v[16:17], v3
	ds_read_b64 v[10:11], v4
	ds_read_b64 v[6:7], v5
	v_add_u32_e32 v2, s90, v154
	v_add_u32_e32 v3, s90, v155
	v_add_u32_e32 v4, s90, v156
	v_lshl_add_u32 v223, s76, 6, v175
	v_add_u32_e32 v116, s90, v157
	ds_read_b64 v[12:13], v2
	ds_read_b64 v[8:9], v3
	ds_read_b64 v[4:5], v4
	ds_read_b64 v[2:3], v116
	ds_read_b128 v[224:227], v223
	v_cndmask_b32_e64 v119, v82, v80, s[88:89]
	v_cndmask_b32_e64 v117, v83, v81, s[88:89]
	ds_read_b128 v[228:231], v223 offset:16
	ds_read_b128 v[232:235], v223 offset:32
	ds_read_b128 v[236:239], v223 offset:48
	s_waitcnt lgkmcnt(0)
	v_fma_f32 v116, v134, v224, v119
	v_fmac_f32_e32 v116, v132, v225
	v_fma_f32 v221, v135, v224, v117
	v_fmac_f32_e32 v116, v128, v226
	v_fmac_f32_e32 v221, v133, v225
	v_fmac_f32_e32 v116, v124, v227
	v_fmac_f32_e32 v221, v129, v226
	v_fmac_f32_e32 v116, v130, v228
	v_fmac_f32_e32 v221, v125, v227
	v_fmac_f32_e32 v116, v126, v229
	v_fmac_f32_e32 v221, v131, v228
	v_fmac_f32_e32 v116, v120, v230
	v_fmac_f32_e32 v221, v127, v229
	v_fmac_f32_e32 v116, v14, v231
	v_fmac_f32_e32 v221, v121, v230
	v_fmac_f32_e32 v116, v122, v232
	v_fmac_f32_e32 v221, v15, v231
	v_fmac_f32_e32 v116, v16, v233
	v_fmac_f32_e32 v221, v123, v232
	v_fmac_f32_e32 v116, v10, v234
	v_fmac_f32_e32 v221, v17, v233
	v_fmac_f32_e32 v116, v6, v235
	v_fmac_f32_e32 v221, v11, v234
	v_fmac_f32_e32 v116, v12, v236
	v_fmac_f32_e32 v221, v7, v235
	v_fmac_f32_e32 v116, v8, v237
	v_fmac_f32_e32 v221, v13, v236
	v_fmac_f32_e32 v116, v4, v238
	v_fmac_f32_e32 v221, v9, v237
	v_fmac_f32_e32 v116, v2, v239
	v_fmac_f32_e32 v221, v5, v238
	v_mul_f32_e64 v118, |v116|, s96
	v_exp_f32_e32 v118, v118
	v_fmac_f32_e32 v221, v3, v239
	v_mul_f32_e64 v222, |v221|, s96
	v_exp_f32_e32 v222, v222
	v_add_f32_e32 v118, 1.0, v118
	v_log_f32_e32 v118, v118
	v_min_f32_e32 v116, 0, v116
	v_add_f32_e32 v222, 1.0, v222
	v_log_f32_e32 v222, v222
	v_fmac_f32_e32 v116, 0xbf317218, v118
	v_mul_f32_e32 v118, 0x3d800000, v116
	v_min_f32_e32 v116, 0, v221
	v_fmac_f32_e32 v116, 0xbf317218, v222
	v_mul_f32_e32 v116, 0x3d800000, v116
	ds_read_b128 v[224:227], v223 offset:128
	ds_read_b128 v[228:231], v223 offset:144
	ds_read_b128 v[232:235], v223 offset:160
	ds_read_b128 v[236:239], v223 offset:176
	s_waitcnt lgkmcnt(3)
; #define LAS __attribute__((address_space(3)))
; DI float logsigmoid_fast(float z) { return fminf(z, 0.f) - 0.6931471805599453f * __builtin_amdgcn_logf(1.0f + __builtin_amdgcn_exp2f(-fabsf(z) * LOG2E)); }
; DI void phase_gla_prep(const Params& P, int l, int bid, int nb, LAS unsigned char* lds) {
;     ...
;             for (int r = 0; r < 8; ++r) { float z0 = bb.x, z1 = bb.y; const LAS float* lr = (const LAS float*)(lds + PP_LR) + (rg * 8 + r) * 32 + dir * 16;
; #pragma unroll
;                 for (int k4 = 0; k4 < 4; ++k4) { const f32x4 t = *(const LAS f32x4*)(lr + k4 * 4);
; #pragma unroll
;                     for (int u = 0; u < 4; ++u) { z0 += t[u] * w0[k4 * 4 + u]; z1 += t[u] * w1[k4 * 4 + u]; } }
;                 g0[r] = logsigmoid_fast(z0) * 0.0625f; g1[r] = logsigmoid_fast(z1) * 0.0625f; __builtin_amdgcn_sched_barrier(0); }
	v_fma_f32 v221, v134, v224, v119
	v_fma_f32 v222, v135, v224, v117
	v_fmac_f32_e32 v221, v132, v225
	v_fmac_f32_e32 v222, v133, v225
	v_fmac_f32_e32 v221, v128, v226
	v_fmac_f32_e32 v222, v129, v226
	v_fmac_f32_e32 v221, v124, v227
	v_fmac_f32_e32 v222, v125, v227
	s_waitcnt lgkmcnt(2)
	v_fmac_f32_e32 v221, v130, v228
	v_fmac_f32_e32 v222, v131, v228
	v_fmac_f32_e32 v221, v126, v229
	v_fmac_f32_e32 v222, v127, v229
	v_fmac_f32_e32 v221, v120, v230
	v_fmac_f32_e32 v222, v121, v230
	v_fmac_f32_e32 v221, v14, v231
	v_fmac_f32_e32 v222, v15, v231
	s_waitcnt lgkmcnt(1)
	v_fmac_f32_e32 v221, v122, v232
	v_fmac_f32_e32 v222, v123, v232
	v_fmac_f32_e32 v221, v16, v233
	v_fmac_f32_e32 v222, v17, v233
	v_fmac_f32_e32 v221, v10, v234
	v_fmac_f32_e32 v222, v11, v234
	v_fmac_f32_e32 v221, v6, v235
	v_fmac_f32_e32 v222, v7, v235
	s_waitcnt lgkmcnt(0)
	v_fmac_f32_e32 v221, v12, v236
	v_fmac_f32_e32 v222, v13, v236
	v_fmac_f32_e32 v221, v8, v237
	v_fmac_f32_e32 v222, v9, v237
	v_fmac_f32_e32 v221, v4, v238
	v_fmac_f32_e32 v222, v5, v238
	v_fmac_f32_e32 v221, v2, v239
	v_fmac_f32_e32 v222, v3, v239
	v_mul_f32_e64 v224, |v221|, s96
	v_mul_f32_e64 v225, |v222|, s96
	v_exp_f32_e32 v224, v224
	v_exp_f32_e32 v225, v225
	v_min_f32_e32 v221, 0, v221
	v_min_f32_e32 v222, 0, v222
	v_add_f32_e32 v224, 1.0, v224
	v_add_f32_e32 v225, 1.0, v225
	v_log_f32_e32 v224, v224
	v_log_f32_e32 v225, v225
	v_fmac_f32_e32 v221, 0xbf317218, v224
	v_fmac_f32_e32 v222, 0xbf317218, v225
	v_mul_f32_e32 v221, 0x3d800000, v221
	v_mul_f32_e32 v222, 0x3d800000, v222
	ds_read_b128 v[224:227], v223 offset:256
	ds_read_b128 v[228:231], v223 offset:272
	ds_read_b128 v[232:235], v223 offset:288
	ds_read_b128 v[236:239], v223 offset:304
	s_waitcnt lgkmcnt(3)
	v_fma_f32 v240, v134, v224, v119
	v_fma_f32 v224, v135, v224, v117
	v_fmac_f32_e32 v240, v132, v225
	v_fmac_f32_e32 v224, v133, v225
	v_fmac_f32_e32 v240, v128, v226
	v_fmac_f32_e32 v224, v129, v226
	v_fmac_f32_e32 v240, v124, v227
	v_fmac_f32_e32 v224, v125, v227
	s_waitcnt lgkmcnt(2)
	v_fmac_f32_e32 v240, v130, v228
	v_fmac_f32_e32 v224, v131, v228
	v_fmac_f32_e32 v240, v126, v229
	v_fmac_f32_e32 v224, v127, v229
	v_fmac_f32_e32 v240, v120, v230
	v_fmac_f32_e32 v224, v121, v230
	v_fmac_f32_e32 v240, v14, v231
	v_fmac_f32_e32 v224, v15, v231
	s_waitcnt lgkmcnt(1)
	v_fmac_f32_e32 v240, v122, v232
	v_fmac_f32_e32 v224, v123, v232
	v_fmac_f32_e32 v240, v16, v233
	v_fmac_f32_e32 v224, v17, v233
	v_fmac_f32_e32 v240, v10, v234
	v_fmac_f32_e32 v224, v11, v234
	v_fmac_f32_e32 v240, v6, v235
	v_fmac_f32_e32 v224, v7, v235
	s_waitcnt lgkmcnt(0)
	v_fmac_f32_e32 v240, v12, v236
	v_fmac_f32_e32 v224, v13, v236
	v_fmac_f32_e32 v240, v8, v237
	v_fmac_f32_e32 v224, v9, v237
	v_fmac_f32_e32 v240, v4, v238
	v_fmac_f32_e32 v224, v5, v238
	v_fmac_f32_e32 v240, v2, v239
	v_fmac_f32_e32 v224, v3, v239
	v_mul_f32_e64 v225, |v240|, s96
	v_mul_f32_e64 v226, |v224|, s96
	v_exp_f32_e32 v225, v225
	v_exp_f32_e32 v226, v226
	v_min_f32_e32 v227, 0, v240
	v_min_f32_e32 v224, 0, v224
	v_add_f32_e32 v225, 1.0, v225
	v_add_f32_e32 v226, 1.0, v226
	v_log_f32_e32 v225, v225
	v_log_f32_e32 v226, v226
	v_fmac_f32_e32 v227, 0xbf317218, v225
	v_fmac_f32_e32 v224, 0xbf317218, v226
	v_mul_f32_e32 v225, 0x3d800000, v227
	v_mul_f32_e32 v224, 0x3d800000, v224
	ds_read_b128 v[226:229], v223 offset:384
	ds_read_b128 v[230:233], v223 offset:400
	ds_read_b128 v[234:237], v223 offset:416
	ds_read_b128 v[238:241], v223 offset:432
	s_waitcnt lgkmcnt(3)
	v_fma_f32 v242, v134, v226, v119
	v_fma_f32 v226, v135, v226, v117
	v_fmac_f32_e32 v242, v132, v227
	v_fmac_f32_e32 v226, v133, v227
	v_fmac_f32_e32 v242, v128, v228
	v_fmac_f32_e32 v226, v129, v228
	v_fmac_f32_e32 v242, v124, v229
	v_fmac_f32_e32 v226, v125, v229
	s_waitcnt lgkmcnt(2)
	v_fmac_f32_e32 v242, v130, v230
	v_fmac_f32_e32 v226, v131, v230
	v_fmac_f32_e32 v242, v126, v231
	v_fmac_f32_e32 v226, v127, v231
	v_fmac_f32_e32 v242, v120, v232
	v_fmac_f32_e32 v226, v121, v232
	v_fmac_f32_e32 v242, v14, v233
	v_fmac_f32_e32 v226, v15, v233
	s_waitcnt lgkmcnt(1)
	v_fmac_f32_e32 v242, v122, v234
	v_fmac_f32_e32 v226, v123, v234
	v_fmac_f32_e32 v242, v16, v235
	v_fmac_f32_e32 v226, v17, v235
	v_fmac_f32_e32 v242, v10, v236
	v_fmac_f32_e32 v226, v11, v236
	v_fmac_f32_e32 v242, v6, v237
	v_fmac_f32_e32 v226, v7, v237
	s_waitcnt lgkmcnt(0)
	v_fmac_f32_e32 v242, v12, v238
	v_fmac_f32_e32 v226, v13, v238
	v_fmac_f32_e32 v242, v8, v239
	v_fmac_f32_e32 v226, v9, v239
	v_fmac_f32_e32 v242, v4, v240
	v_fmac_f32_e32 v226, v5, v240
	v_fmac_f32_e32 v242, v2, v241
	v_fmac_f32_e32 v226, v3, v241
	v_mul_f32_e64 v227, |v242|, s96
	v_mul_f32_e64 v228, |v226|, s96
	v_exp_f32_e32 v227, v227
	v_exp_f32_e32 v228, v228
	v_min_f32_e32 v229, 0, v242
	v_min_f32_e32 v226, 0, v226
	v_add_f32_e32 v227, 1.0, v227
	v_add_f32_e32 v228, 1.0, v228
	v_log_f32_e32 v227, v227
	v_log_f32_e32 v228, v228
	v_fmac_f32_e32 v229, 0xbf317218, v227
	v_fmac_f32_e32 v226, 0xbf317218, v228
	v_mul_f32_e32 v227, 0x3d800000, v229
	v_mul_f32_e32 v226, 0x3d800000, v226
	ds_read_b128 v[228:231], v223 offset:512
	ds_read_b128 v[232:235], v223 offset:528
	ds_read_b128 v[236:239], v223 offset:544
	ds_read_b128 v[240:243], v223 offset:560
	s_waitcnt lgkmcnt(3)
	v_fma_f32 v244, v134, v228, v119
	v_fma_f32 v228, v135, v228, v117
	v_fmac_f32_e32 v244, v132, v229
	v_fmac_f32_e32 v228, v133, v229
	v_fmac_f32_e32 v244, v128, v230
	v_fmac_f32_e32 v228, v129, v230
	v_fmac_f32_e32 v244, v124, v231
	v_fmac_f32_e32 v228, v125, v231
	s_waitcnt lgkmcnt(2)
	v_fmac_f32_e32 v244, v130, v232
	v_fmac_f32_e32 v228, v131, v232
	v_fmac_f32_e32 v244, v126, v233
	v_fmac_f32_e32 v228, v127, v233
	v_fmac_f32_e32 v244, v120, v234
	v_fmac_f32_e32 v228, v121, v234
	v_fmac_f32_e32 v244, v14, v235
	v_fmac_f32_e32 v228, v15, v235
	s_waitcnt lgkmcnt(1)
; #define LAS __attribute__((address_space(3)))
; DI float logsigmoid_fast(float z) { return fminf(z, 0.f) - 0.6931471805599453f * __builtin_amdgcn_logf(1.0f + __builtin_amdgcn_exp2f(-fabsf(z) * LOG2E)); }
; DI void phase_gla_prep(const Params& P, int l, int bid, int nb, LAS unsigned char* lds) {
;     ...
;             for (int r = 0; r < 8; ++r) { float z0 = bb.x, z1 = bb.y; const LAS float* lr = (const LAS float*)(lds + PP_LR) + (rg * 8 + r) * 32 + dir * 16;
; #pragma unroll
;                 for (int k4 = 0; k4 < 4; ++k4) { const f32x4 t = *(const LAS f32x4*)(lr + k4 * 4);
; #pragma unroll
;                     for (int u = 0; u < 4; ++u) { z0 += t[u] * w0[k4 * 4 + u]; z1 += t[u] * w1[k4 * 4 + u]; } }
;                 g0[r] = logsigmoid_fast(z0) * 0.0625f; g1[r] = logsigmoid_fast(z1) * 0.0625f; __builtin_amdgcn_sched_barrier(0); }
;             float tot0, tot1;
;             if (dir == 0) {
	v_fmac_f32_e32 v244, v122, v236
	v_fmac_f32_e32 v228, v123, v236
	v_fmac_f32_e32 v244, v16, v237
	v_fmac_f32_e32 v228, v17, v237
	v_fmac_f32_e32 v244, v10, v238
	v_fmac_f32_e32 v228, v11, v238
	v_fmac_f32_e32 v244, v6, v239
	v_fmac_f32_e32 v228, v7, v239
	s_waitcnt lgkmcnt(0)
	v_fmac_f32_e32 v244, v12, v240
	v_fmac_f32_e32 v228, v13, v240
	v_fmac_f32_e32 v244, v8, v241
	v_fmac_f32_e32 v228, v9, v241
	v_fmac_f32_e32 v244, v4, v242
	v_fmac_f32_e32 v228, v5, v242
	v_fmac_f32_e32 v244, v2, v243
	v_fmac_f32_e32 v228, v3, v243
	v_mul_f32_e64 v229, |v244|, s96
	v_mul_f32_e64 v230, |v228|, s96
	v_exp_f32_e32 v229, v229
	v_exp_f32_e32 v230, v230
	v_min_f32_e32 v231, 0, v244
	v_min_f32_e32 v228, 0, v228
	v_add_f32_e32 v229, 1.0, v229
	v_add_f32_e32 v230, 1.0, v230
	v_log_f32_e32 v229, v229
	v_log_f32_e32 v230, v230
	v_fmac_f32_e32 v231, 0xbf317218, v229
	v_fmac_f32_e32 v228, 0xbf317218, v230
	v_mul_f32_e32 v229, 0x3d800000, v231
	v_mul_f32_e32 v228, 0x3d800000, v228
	ds_read_b128 v[230:233], v223 offset:640
	ds_read_b128 v[234:237], v223 offset:656
	ds_read_b128 v[238:241], v223 offset:672
	ds_read_b128 v[242:245], v223 offset:688
	s_waitcnt lgkmcnt(3)
	v_fma_f32 v246, v134, v230, v119
	v_fma_f32 v230, v135, v230, v117
	v_fmac_f32_e32 v246, v132, v231
	v_fmac_f32_e32 v230, v133, v231
	v_fmac_f32_e32 v246, v128, v232
	v_fmac_f32_e32 v230, v129, v232
	v_fmac_f32_e32 v246, v124, v233
	v_fmac_f32_e32 v230, v125, v233
	s_waitcnt lgkmcnt(2)
	v_fmac_f32_e32 v246, v130, v234
	v_fmac_f32_e32 v230, v131, v234
	v_fmac_f32_e32 v246, v126, v235
	v_fmac_f32_e32 v230, v127, v235
	v_fmac_f32_e32 v246, v120, v236
	v_fmac_f32_e32 v230, v121, v236
	v_fmac_f32_e32 v246, v14, v237
	v_fmac_f32_e32 v230, v15, v237
	s_waitcnt lgkmcnt(1)
	v_fmac_f32_e32 v246, v122, v238
	v_fmac_f32_e32 v230, v123, v238
	v_fmac_f32_e32 v246, v16, v239
	v_fmac_f32_e32 v230, v17, v239
	v_fmac_f32_e32 v246, v10, v240
	v_fmac_f32_e32 v230, v11, v240
	v_fmac_f32_e32 v246, v6, v241
	v_fmac_f32_e32 v230, v7, v241
	s_waitcnt lgkmcnt(0)
	v_fmac_f32_e32 v246, v12, v242
	v_fmac_f32_e32 v230, v13, v242
	v_fmac_f32_e32 v246, v8, v243
	v_fmac_f32_e32 v230, v9, v243
	v_fmac_f32_e32 v246, v4, v244
	v_fmac_f32_e32 v230, v5, v244
	v_fmac_f32_e32 v246, v2, v245
	v_fmac_f32_e32 v230, v3, v245
	v_mul_f32_e64 v231, |v246|, s96
	v_mul_f32_e64 v232, |v230|, s96
	v_exp_f32_e32 v231, v231
	v_exp_f32_e32 v232, v232
	v_min_f32_e32 v233, 0, v246
	v_min_f32_e32 v230, 0, v230
	v_add_f32_e32 v231, 1.0, v231
	v_add_f32_e32 v232, 1.0, v232
	v_log_f32_e32 v231, v231
	v_log_f32_e32 v232, v232
	v_fmac_f32_e32 v233, 0xbf317218, v231
	v_fmac_f32_e32 v230, 0xbf317218, v232
	v_mul_f32_e32 v231, 0x3d800000, v233
	v_mul_f32_e32 v230, 0x3d800000, v230
	ds_read_b128 v[232:235], v223 offset:768
	ds_read_b128 v[236:239], v223 offset:784
	ds_read_b128 v[240:243], v223 offset:800
	ds_read_b128 v[244:247], v223 offset:816
	s_waitcnt lgkmcnt(3)
	v_fma_f32 v248, v134, v232, v119
	v_fma_f32 v232, v135, v232, v117
	v_fmac_f32_e32 v248, v132, v233
	v_fmac_f32_e32 v232, v133, v233
	v_fmac_f32_e32 v248, v128, v234
	v_fmac_f32_e32 v232, v129, v234
	v_fmac_f32_e32 v248, v124, v235
	v_fmac_f32_e32 v232, v125, v235
	s_waitcnt lgkmcnt(2)
	v_fmac_f32_e32 v248, v130, v236
	v_fmac_f32_e32 v232, v131, v236
	v_fmac_f32_e32 v248, v126, v237
	v_fmac_f32_e32 v232, v127, v237
	v_fmac_f32_e32 v248, v120, v238
	v_fmac_f32_e32 v232, v121, v238
	v_fmac_f32_e32 v248, v14, v239
	v_fmac_f32_e32 v232, v15, v239
	s_waitcnt lgkmcnt(1)
	v_fmac_f32_e32 v248, v122, v240
	v_fmac_f32_e32 v232, v123, v240
	v_fmac_f32_e32 v248, v16, v241
	v_fmac_f32_e32 v232, v17, v241
	v_fmac_f32_e32 v248, v10, v242
	v_fmac_f32_e32 v232, v11, v242
	v_fmac_f32_e32 v248, v6, v243
	v_fmac_f32_e32 v232, v7, v243
	s_waitcnt lgkmcnt(0)
	v_fmac_f32_e32 v248, v12, v244
	v_fmac_f32_e32 v232, v13, v244
	v_fmac_f32_e32 v248, v8, v245
	v_fmac_f32_e32 v232, v9, v245
	v_fmac_f32_e32 v248, v4, v246
	v_fmac_f32_e32 v232, v5, v246
	v_fmac_f32_e32 v248, v2, v247
	v_fmac_f32_e32 v232, v3, v247
	v_mul_f32_e64 v233, |v248|, s96
	v_mul_f32_e64 v234, |v232|, s96
	v_exp_f32_e32 v233, v233
	v_exp_f32_e32 v234, v234
	v_min_f32_e32 v235, 0, v248
	v_min_f32_e32 v232, 0, v232
	v_add_f32_e32 v233, 1.0, v233
	v_add_f32_e32 v234, 1.0, v234
	v_log_f32_e32 v233, v233
	v_log_f32_e32 v234, v234
	v_fmac_f32_e32 v235, 0xbf317218, v233
	v_fmac_f32_e32 v232, 0xbf317218, v234
	v_mul_f32_e32 v233, 0x3d800000, v235
	v_mul_f32_e32 v232, 0x3d800000, v232
	ds_read_b128 v[234:237], v223 offset:896
	ds_read_b128 v[238:241], v223 offset:912
	ds_read_b128 v[242:245], v223 offset:928
	ds_read_b128 v[246:249], v223 offset:944
	s_waitcnt lgkmcnt(3)
	v_fmac_f32_e32 v119, v134, v234
	v_fmac_f32_e32 v117, v135, v234
	v_fmac_f32_e32 v119, v132, v235
	v_fmac_f32_e32 v117, v133, v235
	v_fmac_f32_e32 v119, v128, v236
	v_fmac_f32_e32 v117, v129, v236
	v_fmac_f32_e32 v119, v124, v237
	v_fmac_f32_e32 v117, v125, v237
	s_waitcnt lgkmcnt(2)
	v_fmac_f32_e32 v119, v130, v238
	v_fmac_f32_e32 v117, v131, v238
	v_fmac_f32_e32 v119, v126, v239
	v_fmac_f32_e32 v117, v127, v239
	v_fmac_f32_e32 v119, v120, v240
	v_fmac_f32_e32 v117, v121, v240
	v_fmac_f32_e32 v119, v14, v241
	v_fmac_f32_e32 v117, v15, v241
	s_waitcnt lgkmcnt(1)
	v_fmac_f32_e32 v119, v122, v242
	v_fmac_f32_e32 v117, v123, v242
	v_fmac_f32_e32 v119, v16, v243
	v_fmac_f32_e32 v117, v17, v243
	v_fmac_f32_e32 v119, v10, v244
	v_fmac_f32_e32 v117, v11, v244
	v_fmac_f32_e32 v119, v6, v245
	v_fmac_f32_e32 v117, v7, v245
	s_waitcnt lgkmcnt(0)
	v_fmac_f32_e32 v119, v12, v246
	v_fmac_f32_e32 v117, v13, v246
	v_fmac_f32_e32 v119, v8, v247
	v_fmac_f32_e32 v117, v9, v247
	v_fmac_f32_e32 v119, v4, v248
	v_fmac_f32_e32 v117, v5, v248
	v_fmac_f32_e32 v119, v2, v249
	v_mul_f32_e64 v2, |v119|, s96
	v_fmac_f32_e32 v117, v3, v249
	v_exp_f32_e32 v2, v2
	v_mul_f32_e64 v3, |v117|, s96
	v_exp_f32_e32 v3, v3
	v_min_f32_e32 v4, 0, v119
	v_add_f32_e32 v2, 1.0, v2
	v_log_f32_e32 v2, v2
	v_add_f32_e32 v3, 1.0, v3
	v_log_f32_e32 v3, v3
	v_fmac_f32_e32 v4, 0xbf317218, v2
	v_min_f32_e32 v2, 0, v117
	v_fmac_f32_e32 v2, 0xbf317218, v3
	v_mul_f32_e32 v123, 0x3d800000, v4
	v_mul_f32_e32 v121, 0x3d800000, v2
	s_and_b64 vcc, exec, s[88:89]
	s_mov_b64 s[90:91], -1
	s_cbranch_vccnz .LBB0_346
; DI void phase_gla_prep(const Params& P, int l, int bid, int nb, LAS unsigned char* lds) {
;     ...
;             } else {
; #pragma unroll
;                 for (int r = 6; r >= 0; --r) { g0[r] += g0[r + 1]; g1[r] += g1[r + 1]; }
;                 float s0 = g0[0], s1 = g1[0];
; #pragma unroll
;                 for (int o = 8; o < 64; o <<= 1) { const float t0 = __shfl_down(s0, o), t1 = __shfl_down(s1, o); if (lane + o < 64) { s0 += t0; s1 += t1; } }
;                 const float e0 = s0 - g0[0], e1 = s1 - g1[0];
; #pragma unroll
;                 for (int r = 0; r < 8; ++r) { g0[r] += e0; g1[r] += e1; }
;                 tot0 = __shfl(s0, dpl); tot1 = __shfl(s1, dpl);
	v_add_f32_e32 v122, v233, v123
	v_add_f32_e32 v120, v232, v121
	v_add_f32_e32 v3, v231, v122
	v_add_f32_e32 v2, v229, v3
	v_add_f32_e32 v13, v230, v120
	v_add_f32_e32 v5, v227, v2
	v_add_f32_e32 v12, v228, v13
	v_add_f32_e32 v4, v225, v5
	v_add_f32_e32 v125, v226, v12
	v_add_f32_e32 v11, v221, v4
	v_add_f32_e32 v124, v224, v125
	v_add_f32_e32 v10, v118, v11
	v_add_f32_e32 v127, v222, v124
	ds_bpermute_b32 v6, v79, v10
	v_add_f32_e32 v126, v116, v127
	ds_bpermute_b32 v7, v79, v126
	s_mov_b64 s[90:91], 0
	s_waitcnt lgkmcnt(1)
	v_add_f32_e32 v6, v10, v6
	v_cndmask_b32_e64 v6, v10, v6, s[2:3]
	s_waitcnt lgkmcnt(0)
	v_add_f32_e32 v7, v126, v7
	ds_bpermute_b32 v8, v215, v6
	v_cndmask_b32_e64 v7, v126, v7, s[2:3]
	ds_bpermute_b32 v9, v215, v7
	s_waitcnt lgkmcnt(1)
	v_add_f32_e32 v8, v6, v8
	v_cndmask_b32_e64 v6, v6, v8, s[4:5]
	s_waitcnt lgkmcnt(0)
	v_add_f32_e32 v9, v7, v9
	ds_bpermute_b32 v8, v211, v6
	v_cndmask_b32_e64 v7, v7, v9, s[4:5]
	ds_bpermute_b32 v9, v211, v7
	s_waitcnt lgkmcnt(1)
	v_add_f32_e32 v8, v6, v8
	v_cndmask_b32_e64 v15, v6, v8, s[6:7]
	s_waitcnt lgkmcnt(0)
	v_add_f32_e32 v6, v7, v9
	v_cndmask_b32_e64 v117, v7, v6, s[6:7]
	v_sub_f32_e32 v128, v117, v126
	v_pk_add_f32 v[16:17], v[120:121], v[128:129] op_sel_hi:[1,0]
	ds_bpermute_b32 v119, v216, v15
	ds_bpermute_b32 v120, v216, v117
	v_sub_f32_e32 v14, v15, v10
	v_pk_add_f32 v[8:9], v[122:123], v[14:15] op_sel_hi:[1,0]
	v_pk_add_f32 v[6:7], v[2:3], v[14:15] op_sel_hi:[1,0]
	v_pk_add_f32 v[4:5], v[4:5], v[14:15] op_sel_hi:[1,0]
	v_pk_add_f32 v[2:3], v[10:11], v[14:15] op_sel_hi:[1,0]
	v_pk_add_f32 v[14:15], v[12:13], v[128:129] op_sel_hi:[1,0]
	v_pk_add_f32 v[12:13], v[124:125], v[128:129] op_sel_hi:[1,0]
	v_pk_add_f32 v[10:11], v[126:127], v[128:129] op_sel_hi:[1,0]
